# k-fastest tile order also in the six smaller weight transposes of the prologue
# baseline (speedup 1.0000x reference)
; DEV int tid_() { int t = threadIdx.x; asm volatile("" : "+v"(t)); return t; }
; DEV int bid_() { int t = blockIdx.x; asm volatile("" : "+s"(t)); return t; }
; DEV int gdim_() { int t = gridDim.x; asm volatile("" : "+s"(t)); return t; }
; __device__ void transpose_convert(const float* __restrict__ src, int K, int N, u16* __restrict__ dst, char* smem) {
;   float* tile = (float*)smem;
;   const int tilesN = N >> 6, ntiles = (K >> 6) * tilesN;
;   const int tid = tid_();
;   for (int t = bid_(); t < ntiles; t += gdim_()) {
;     const int k0 = (t / tilesN) << 6, n0 = (t % tilesN) << 6;
;     __syncthreads();
;     const int ty = tid >> 4, tx = tid & 15;
; #pragma unroll
;     for (int pp = 0; pp < 4; ++pp) {
;       int k = ty + 16 * pp;
;       float4 v = *(const float4*)(src + (size_t)(k0 + k) * N + n0 + tx * 4);
;       float* d = tile + k * 65 + tx * 4;
;       d[0] = v.x; d[1] = v.y; d[2] = v.z; d[3] = v.w;
;     }
;     __syncthreads();
;     const int n = tid >> 2, ks = (tid & 3) * 16;
;     unsigned o[8];
; #pragma unroll
;     for (int e = 0; e < 8; ++e) o[e] = pack2(tile[(ks + 2 * e) * 65 + n], tile[(ks + 2 * e + 1) * 65 + n]);
;     uint4* d = (uint4*)(dst + (size_t)(n0 + n) * K + k0 + ks);
;     d[0] = make_uint4(o[0], o[1], o[2], o[3]);
;     d[1] = make_uint4(o[4], o[5], o[6], o[7]);
;   }
.LBB0_25:
	s_and_b32 s0, s6, 31
	s_lshl_b32 s0, s0, 6
	s_lshr_b32 s1, s6, 5
	v_add_u32_e32 v20, s0, v1
	s_lshl_b32 s12, s1, 6
	v_add_u32_e32 v22, 16, v20
	s_ashr_i32 s13, s12, 31
	v_ashrrev_i32_e32 v21, 31, v20
	v_add_u32_e32 v24, 32, v20
	v_add_u32_e32 v26, 48, v20
	v_ashrrev_i32_e32 v23, 31, v22
	v_lshl_add_u64 v[28:29], s[12:13], 2, v[6:7]
	v_lshlrev_b64 v[20:21], 13, v[20:21]
	v_ashrrev_i32_e32 v25, 31, v24
	v_ashrrev_i32_e32 v27, 31, v26
	v_lshlrev_b64 v[30:31], 13, v[22:23]
	v_lshl_add_u64 v[20:21], v[28:29], 0, v[20:21]
	v_lshlrev_b64 v[24:25], 13, v[24:25]
	v_lshlrev_b64 v[26:27], 13, v[26:27]
	v_lshl_add_u64 v[36:37], v[28:29], 0, v[30:31]
	s_barrier
	flat_load_dwordx4 v[20:23], v[20:21]
	v_lshl_add_u64 v[38:39], v[28:29], 0, v[24:25]
	v_lshl_add_u64 v[40:41], v[28:29], 0, v[26:27]
	flat_load_dwordx4 v[24:27], v[36:37]
	flat_load_dwordx4 v[28:31], v[38:39]
	flat_load_dwordx4 v[32:35], v[40:41]
	v_add_u32_e32 v36, s12, v8
	v_ashrrev_i32_e32 v37, 31, v36
	v_lshlrev_b64 v[36:37], 12, v[36:37]
	s_ashr_i32 s1, s0, 31
	v_lshl_add_u64 v[36:37], v[2:3], 0, v[36:37]
	v_lshl_add_u64 v[36:37], s[0:1], 1, v[36:37]
	s_mov_b32 s7, s34
	v_lshl_add_u64 v[36:37], v[36:37], 0, v[4:5]
	s_waitcnt vmcnt(0) lgkmcnt(0)
	ds_write2_b32 v10, v20, v21 offset1:1
	ds_write2_b32 v10, v22, v23 offset0:2 offset1:3
	ds_write2_b32 v11, v24, v25 offset1:1
	ds_write2_b32 v12, v26, v27 offset1:1
	ds_write2_b32 v13, v28, v29 offset1:1
	ds_write2_b32 v14, v30, v31 offset1:1
	ds_write2_b32 v15, v32, v33 offset1:1
	ds_write2_b32 v16, v34, v35 offset1:1
	s_waitcnt lgkmcnt(0)
	s_barrier
	ds_read2_b32 v[20:21], v9 offset1:65
	ds_read2_b32 v[22:23], v9 offset0:130 offset1:195
	ds_read2_b32 v[24:25], v17 offset0:4 offset1:69
	ds_read2_b32 v[26:27], v17 offset0:134 offset1:199
	ds_read2_b32 v[28:29], v18 offset0:8 offset1:73
	ds_read2_b32 v[30:31], v18 offset0:138 offset1:203
	ds_read2_b32 v[32:33], v19 offset0:12 offset1:77
	ds_read2_b32 v[34:35], v19 offset0:142 offset1:207
	s_waitcnt lgkmcnt(7)
	v_cvt_pk_bf16_f32 v20, v20, v21
	s_waitcnt lgkmcnt(6)
	v_cvt_pk_bf16_f32 v21, v22, v23
	s_waitcnt lgkmcnt(5)
	v_cvt_pk_bf16_f32 v22, v24, v25
	s_waitcnt lgkmcnt(4)
	v_cvt_pk_bf16_f32 v23, v26, v27
	s_waitcnt lgkmcnt(3)
	v_cvt_pk_bf16_f32 v24, v28, v29
	s_waitcnt lgkmcnt(2)
	v_cvt_pk_bf16_f32 v25, v30, v31
	s_waitcnt lgkmcnt(1)
	v_cvt_pk_bf16_f32 v26, v32, v33
	s_waitcnt lgkmcnt(0)
	v_cvt_pk_bf16_f32 v27, v34, v35
	flat_store_dwordx4 v[36:37], v[20:23]
	flat_store_dwordx4 v[36:37], v[24:27] offset:16
	s_add_i32 s6, s7, s6
	s_cmpk_lt_i32 s6, 0x400
	s_cbranch_scc1 .LBB0_25

; DEV int tid_() { int t = threadIdx.x; asm volatile("" : "+v"(t)); return t; }
; DEV int bid_() { int t = blockIdx.x; asm volatile("" : "+s"(t)); return t; }
; DEV int gdim_() { int t = gridDim.x; asm volatile("" : "+s"(t)); return t; }
; __device__ void transpose_convert(const float* __restrict__ src, int K, int N, u16* __restrict__ dst, char* smem) {
;   float* tile = (float*)smem;
;   const int tilesN = N >> 6, ntiles = (K >> 6) * tilesN;
;   const int tid = tid_();
;   for (int t = bid_(); t < ntiles; t += gdim_()) {
;     const int k0 = (t / tilesN) << 6, n0 = (t % tilesN) << 6;
;     __syncthreads();
;     const int ty = tid >> 4, tx = tid & 15;
; #pragma unroll
;     for (int pp = 0; pp < 4; ++pp) {
;       int k = ty + 16 * pp;
;       float4 v = *(const float4*)(src + (size_t)(k0 + k) * N + n0 + tx * 4);
;       float* d = tile + k * 65 + tx * 4;
;       d[0] = v.x; d[1] = v.y; d[2] = v.z; d[3] = v.w;
;     }
;     __syncthreads();
;     const int n = tid >> 2, ks = (tid & 3) * 16;
;     unsigned o[8];
; #pragma unroll
;     for (int e = 0; e < 8; ++e) o[e] = pack2(tile[(ks + 2 * e) * 65 + n], tile[(ks + 2 * e + 1) * 65 + n]);
;     uint4* d = (uint4*)(dst + (size_t)(n0 + n) * K + k0 + ks);
;     d[0] = make_uint4(o[0], o[1], o[2], o[3]);
;     d[1] = make_uint4(o[4], o[5], o[6], o[7]);
;   }
.LBB0_28:
	s_and_b32 s0, s6, 15
	s_lshl_b32 s0, s0, 6
	s_lshr_b32 s1, s6, 4
	v_add_u32_e32 v22, s0, v8
	s_lshl_b32 s12, s1, 6
	v_add_u32_e32 v24, 16, v22
	s_ashr_i32 s13, s12, 31
	v_ashrrev_i32_e32 v23, 31, v22
	v_add_u32_e32 v26, 32, v22
	v_add_u32_e32 v28, 48, v22
	v_ashrrev_i32_e32 v25, 31, v24
	v_lshl_add_u64 v[30:31], s[12:13], 2, v[6:7]
	v_lshlrev_b64 v[22:23], 13, v[22:23]
	v_ashrrev_i32_e32 v27, 31, v26
	v_ashrrev_i32_e32 v29, 31, v28
	v_lshlrev_b64 v[32:33], 13, v[24:25]
	v_lshl_add_u64 v[22:23], v[30:31], 0, v[22:23]
	v_lshlrev_b64 v[26:27], 13, v[26:27]
	v_lshlrev_b64 v[28:29], 13, v[28:29]
	v_lshl_add_u64 v[38:39], v[30:31], 0, v[32:33]
	s_barrier
	flat_load_dwordx4 v[22:25], v[22:23]
	v_lshl_add_u64 v[40:41], v[30:31], 0, v[26:27]
	v_lshl_add_u64 v[42:43], v[30:31], 0, v[28:29]
	flat_load_dwordx4 v[26:29], v[38:39]
	flat_load_dwordx4 v[30:33], v[40:41]
	flat_load_dwordx4 v[34:37], v[42:43]
	v_add_u32_e32 v38, s12, v9
	v_ashrrev_i32_e32 v39, 31, v38
	v_lshlrev_b64 v[38:39], 11, v[38:39]
	s_ashr_i32 s1, s0, 31
	v_lshl_add_u64 v[38:39], v[2:3], 0, v[38:39]
	v_lshl_add_u64 v[38:39], s[0:1], 1, v[38:39]
	s_mov_b32 s7, s34
	v_lshl_add_u64 v[38:39], v[38:39], 0, v[4:5]
	s_waitcnt vmcnt(0) lgkmcnt(0)
	ds_write2_b32 v11, v22, v23 offset1:1
	ds_write2_b32 v11, v24, v25 offset0:2 offset1:3
	ds_write2_b32 v12, v26, v27 offset1:1
	ds_write2_b32 v13, v28, v29 offset1:1
	ds_write2_b32 v14, v30, v31 offset1:1
	ds_write2_b32 v15, v32, v33 offset1:1
	ds_write2_b32 v16, v34, v35 offset1:1
	ds_write2_b32 v17, v36, v37 offset1:1
	s_waitcnt lgkmcnt(0)
	s_barrier
	ds_read2_b32 v[22:23], v10 offset1:65
	ds_read2_b32 v[24:25], v10 offset0:130 offset1:195
	ds_read2_b32 v[26:27], v18 offset0:4 offset1:69
	ds_read2_b32 v[28:29], v18 offset0:134 offset1:199
	ds_read2_b32 v[30:31], v19 offset0:8 offset1:73
	ds_read2_b32 v[32:33], v19 offset0:138 offset1:203
	ds_read2_b32 v[34:35], v20 offset0:12 offset1:77
	ds_read2_b32 v[36:37], v20 offset0:142 offset1:207
	s_waitcnt lgkmcnt(7)
	v_cvt_pk_bf16_f32 v22, v22, v23
	s_waitcnt lgkmcnt(6)
	v_cvt_pk_bf16_f32 v23, v24, v25
	s_waitcnt lgkmcnt(5)
	v_cvt_pk_bf16_f32 v24, v26, v27
	s_waitcnt lgkmcnt(4)
	v_cvt_pk_bf16_f32 v25, v28, v29
	s_waitcnt lgkmcnt(3)
	v_cvt_pk_bf16_f32 v26, v30, v31
	s_waitcnt lgkmcnt(2)
	v_cvt_pk_bf16_f32 v27, v32, v33
	s_waitcnt lgkmcnt(1)
	v_cvt_pk_bf16_f32 v28, v34, v35
	s_waitcnt lgkmcnt(0)
	v_cvt_pk_bf16_f32 v29, v36, v37
	flat_store_dwordx4 v[38:39], v[22:25]
	flat_store_dwordx4 v[38:39], v[26:29] offset:16
	s_add_i32 s6, s7, s6
	s_cmpk_lt_i32 s6, 0x200
	s_cbranch_scc1 .LBB0_28

; DEV int tid_() { int t = threadIdx.x; asm volatile("" : "+v"(t)); return t; }
; DEV int bid_() { int t = blockIdx.x; asm volatile("" : "+s"(t)); return t; }
; DEV int gdim_() { int t = gridDim.x; asm volatile("" : "+s"(t)); return t; }
; __device__ void transpose_convert(const float* __restrict__ src, int K, int N, u16* __restrict__ dst, char* smem) {
;   float* tile = (float*)smem;
;   const int tilesN = N >> 6, ntiles = (K >> 6) * tilesN;
;   const int tid = tid_();
;   for (int t = bid_(); t < ntiles; t += gdim_()) {
;     const int k0 = (t / tilesN) << 6, n0 = (t % tilesN) << 6;
;     __syncthreads();
;     const int ty = tid >> 4, tx = tid & 15;
; #pragma unroll
;     for (int pp = 0; pp < 4; ++pp) {
;       int k = ty + 16 * pp;
;       float4 v = *(const float4*)(src + (size_t)(k0 + k) * N + n0 + tx * 4);
;       float* d = tile + k * 65 + tx * 4;
;       d[0] = v.x; d[1] = v.y; d[2] = v.z; d[3] = v.w;
;     }
;     __syncthreads();
;     const int n = tid >> 2, ks = (tid & 3) * 16;
;     unsigned o[8];
; #pragma unroll
;     for (int e = 0; e < 8; ++e) o[e] = pack2(tile[(ks + 2 * e) * 65 + n], tile[(ks + 2 * e + 1) * 65 + n]);
;     uint4* d = (uint4*)(dst + (size_t)(n0 + n) * K + k0 + ks);
;     d[0] = make_uint4(o[0], o[1], o[2], o[3]);
;     d[1] = make_uint4(o[4], o[5], o[6], o[7]);
;   }
.LBB0_34:
	s_and_b32 s0, s6, 31
	s_lshl_b32 s0, s0, 6
	s_lshr_b32 s1, s6, 5
	v_add_u32_e32 v22, s0, v8
	s_lshl_b32 s12, s1, 6
	v_add_u32_e32 v24, 16, v22
	s_ashr_i32 s13, s12, 31
	v_ashrrev_i32_e32 v23, 31, v22
	v_add_u32_e32 v26, 32, v22
	v_add_u32_e32 v28, 48, v22
	v_ashrrev_i32_e32 v25, 31, v24
	v_lshl_add_u64 v[30:31], s[12:13], 2, v[6:7]
	v_lshlrev_b64 v[22:23], 13, v[22:23]
	v_ashrrev_i32_e32 v27, 31, v26
	v_ashrrev_i32_e32 v29, 31, v28
	v_lshlrev_b64 v[32:33], 13, v[24:25]
	v_lshl_add_u64 v[22:23], v[30:31], 0, v[22:23]
	v_lshlrev_b64 v[26:27], 13, v[26:27]
	v_lshlrev_b64 v[28:29], 13, v[28:29]
	v_lshl_add_u64 v[38:39], v[30:31], 0, v[32:33]
	s_barrier
	flat_load_dwordx4 v[22:25], v[22:23]
	v_lshl_add_u64 v[40:41], v[30:31], 0, v[26:27]
	v_lshl_add_u64 v[42:43], v[30:31], 0, v[28:29]
	flat_load_dwordx4 v[26:29], v[38:39]
	flat_load_dwordx4 v[30:33], v[40:41]
	flat_load_dwordx4 v[34:37], v[42:43]
	v_add_u32_e32 v38, s12, v9
	v_ashrrev_i32_e32 v39, 31, v38
	v_lshlrev_b64 v[38:39], 12, v[38:39]
	s_ashr_i32 s1, s0, 31
	v_lshl_add_u64 v[38:39], v[2:3], 0, v[38:39]
	v_lshl_add_u64 v[38:39], s[0:1], 1, v[38:39]
	s_mov_b32 s7, s34
	v_lshl_add_u64 v[38:39], v[38:39], 0, v[4:5]
	s_waitcnt vmcnt(0) lgkmcnt(0)
	ds_write2_b32 v11, v22, v23 offset1:1
	ds_write2_b32 v11, v24, v25 offset0:2 offset1:3
	ds_write2_b32 v12, v26, v27 offset1:1
	ds_write2_b32 v13, v28, v29 offset1:1
	ds_write2_b32 v14, v30, v31 offset1:1
	ds_write2_b32 v15, v32, v33 offset1:1
	ds_write2_b32 v16, v34, v35 offset1:1
	ds_write2_b32 v17, v36, v37 offset1:1
	s_waitcnt lgkmcnt(0)
	s_barrier
	ds_read2_b32 v[22:23], v10 offset1:65
	ds_read2_b32 v[24:25], v10 offset0:130 offset1:195
	ds_read2_b32 v[26:27], v18 offset0:4 offset1:69
	ds_read2_b32 v[28:29], v18 offset0:134 offset1:199
	ds_read2_b32 v[30:31], v19 offset0:8 offset1:73
	ds_read2_b32 v[32:33], v19 offset0:138 offset1:203
	ds_read2_b32 v[34:35], v20 offset0:12 offset1:77
	ds_read2_b32 v[36:37], v20 offset0:142 offset1:207
	s_waitcnt lgkmcnt(7)
	v_cvt_pk_bf16_f32 v22, v22, v23
	s_waitcnt lgkmcnt(6)
	v_cvt_pk_bf16_f32 v23, v24, v25
	s_waitcnt lgkmcnt(5)
	v_cvt_pk_bf16_f32 v24, v26, v27
	s_waitcnt lgkmcnt(4)
	v_cvt_pk_bf16_f32 v25, v28, v29
	s_waitcnt lgkmcnt(3)
	v_cvt_pk_bf16_f32 v26, v30, v31
	s_waitcnt lgkmcnt(2)
	v_cvt_pk_bf16_f32 v27, v32, v33
	s_waitcnt lgkmcnt(1)
	v_cvt_pk_bf16_f32 v28, v34, v35
	s_waitcnt lgkmcnt(0)
	v_cvt_pk_bf16_f32 v29, v36, v37
	flat_store_dwordx4 v[38:39], v[22:25]
	flat_store_dwordx4 v[38:39], v[26:29] offset:16
	s_add_i32 s6, s7, s6
	s_cmpk_lt_i32 s6, 0x400
	s_cbranch_scc1 .LBB0_34

; DEV int tid_() { int t = threadIdx.x; asm volatile("" : "+v"(t)); return t; }
; DEV int bid_() { int t = blockIdx.x; asm volatile("" : "+s"(t)); return t; }
; DEV int gdim_() { int t = gridDim.x; asm volatile("" : "+s"(t)); return t; }
; __device__ void transpose_convert(const float* __restrict__ src, int K, int N, u16* __restrict__ dst, char* smem) {
;   float* tile = (float*)smem;
;   const int tilesN = N >> 6, ntiles = (K >> 6) * tilesN;
;   const int tid = tid_();
;   for (int t = bid_(); t < ntiles; t += gdim_()) {
;     const int k0 = (t / tilesN) << 6, n0 = (t % tilesN) << 6;
;     __syncthreads();
;     const int ty = tid >> 4, tx = tid & 15;
; #pragma unroll
;     for (int pp = 0; pp < 4; ++pp) {
;       int k = ty + 16 * pp;
;       float4 v = *(const float4*)(src + (size_t)(k0 + k) * N + n0 + tx * 4);
;       float* d = tile + k * 65 + tx * 4;
;       d[0] = v.x; d[1] = v.y; d[2] = v.z; d[3] = v.w;
;     }
;     __syncthreads();
;     const int n = tid >> 2, ks = (tid & 3) * 16;
;     unsigned o[8];
; #pragma unroll
;     for (int e = 0; e < 8; ++e) o[e] = pack2(tile[(ks + 2 * e) * 65 + n], tile[(ks + 2 * e + 1) * 65 + n]);
;     uint4* d = (uint4*)(dst + (size_t)(n0 + n) * K + k0 + ks);
;     d[0] = make_uint4(o[0], o[1], o[2], o[3]);
;     d[1] = make_uint4(o[4], o[5], o[6], o[7]);
;   }
.LBB0_40:
	s_and_b32 s0, s6, 3
	s_lshl_b32 s0, s0, 6
	s_lshr_b32 s1, s6, 2
	v_add_u32_e32 v22, s0, v8
	s_lshl_b32 s12, s1, 6
	v_add_u32_e32 v24, 16, v22
	s_ashr_i32 s13, s12, 31
	v_ashrrev_i32_e32 v23, 31, v22
	v_add_u32_e32 v26, 32, v22
	v_add_u32_e32 v28, 48, v22
	v_ashrrev_i32_e32 v25, 31, v24
	v_lshl_add_u64 v[30:31], s[12:13], 2, v[6:7]
	v_lshlrev_b64 v[22:23], 13, v[22:23]
	v_ashrrev_i32_e32 v27, 31, v26
	v_ashrrev_i32_e32 v29, 31, v28
	v_lshlrev_b64 v[32:33], 13, v[24:25]
	v_lshl_add_u64 v[22:23], v[30:31], 0, v[22:23]
	v_lshlrev_b64 v[26:27], 13, v[26:27]
	v_lshlrev_b64 v[28:29], 13, v[28:29]
	v_lshl_add_u64 v[38:39], v[30:31], 0, v[32:33]
	s_barrier
	flat_load_dwordx4 v[22:25], v[22:23]
	v_lshl_add_u64 v[40:41], v[30:31], 0, v[26:27]
	v_lshl_add_u64 v[42:43], v[30:31], 0, v[28:29]
	flat_load_dwordx4 v[26:29], v[38:39]
	flat_load_dwordx4 v[30:33], v[40:41]
	flat_load_dwordx4 v[34:37], v[42:43]
	v_add_u32_e32 v38, s12, v9
	v_ashrrev_i32_e32 v39, 31, v38
	v_lshlrev_b64 v[38:39], 9, v[38:39]
	s_ashr_i32 s1, s0, 31
	v_lshl_add_u64 v[38:39], v[2:3], 0, v[38:39]
	v_lshl_add_u64 v[38:39], s[0:1], 1, v[38:39]
	s_mov_b32 s7, s34
	v_lshl_add_u64 v[38:39], v[38:39], 0, v[4:5]
	s_waitcnt vmcnt(0) lgkmcnt(0)
	ds_write2_b32 v11, v22, v23 offset1:1
	ds_write2_b32 v11, v24, v25 offset0:2 offset1:3
	ds_write2_b32 v12, v26, v27 offset1:1
	ds_write2_b32 v13, v28, v29 offset1:1
	ds_write2_b32 v14, v30, v31 offset1:1
	ds_write2_b32 v15, v32, v33 offset1:1
	ds_write2_b32 v16, v34, v35 offset1:1
	ds_write2_b32 v17, v36, v37 offset1:1
	s_waitcnt lgkmcnt(0)
	s_barrier
	ds_read2_b32 v[22:23], v10 offset1:65
	ds_read2_b32 v[24:25], v10 offset0:130 offset1:195
	ds_read2_b32 v[26:27], v18 offset0:4 offset1:69
	ds_read2_b32 v[28:29], v18 offset0:134 offset1:199
	ds_read2_b32 v[30:31], v19 offset0:8 offset1:73
	ds_read2_b32 v[32:33], v19 offset0:138 offset1:203
	ds_read2_b32 v[34:35], v20 offset0:12 offset1:77
	ds_read2_b32 v[36:37], v20 offset0:142 offset1:207
	s_waitcnt lgkmcnt(7)
	v_cvt_pk_bf16_f32 v22, v22, v23
	s_waitcnt lgkmcnt(6)
	v_cvt_pk_bf16_f32 v23, v24, v25
	s_waitcnt lgkmcnt(5)
	v_cvt_pk_bf16_f32 v24, v26, v27
	s_waitcnt lgkmcnt(4)
	v_cvt_pk_bf16_f32 v25, v28, v29
	s_waitcnt lgkmcnt(3)
	v_cvt_pk_bf16_f32 v26, v30, v31
	s_waitcnt lgkmcnt(2)
	v_cvt_pk_bf16_f32 v27, v32, v33
	s_waitcnt lgkmcnt(1)
	v_cvt_pk_bf16_f32 v28, v34, v35
	s_waitcnt lgkmcnt(0)
	v_cvt_pk_bf16_f32 v29, v36, v37
	flat_store_dwordx4 v[38:39], v[22:25]
	flat_store_dwordx4 v[38:39], v[26:29] offset:16
	s_add_i32 s6, s7, s6
	s_cmpk_lt_i32 s6, 0x80
	s_cbranch_scc1 .LBB0_40
